# fused final RMSNorm, and the now-unneeded last grid barrier skipped (kernel ends after the last GEMM phase)
# speedup vs baseline: 1.0303x; 1.0022x over previous
.LBB0_1005:
	s_branch .LBB0_1060
	s_waitcnt vmcnt(0)
	s_waitcnt lgkmcnt(0)
	s_barrier
	s_mov_b64 s[0:1], exec
	v_readlane_b32 s2, v255, 6
	v_readlane_b32 s3, v255, 7
	s_and_b64 s[2:3], s[0:1], s[2:3]
	s_mov_b64 exec, s[2:3]
	s_cbranch_execz .LBB0_1057
	s_add_i32 s2, 0, 0x20000
	v_mov_b32_e32 v0, s2
	s_waitcnt vmcnt(0) expcnt(0) lgkmcnt(0)
	ds_read_b32 v2, v0
	s_add_i32 s2, 0, 0x20004
	v_mov_b32_e32 v0, s2
	ds_read_b32 v0, v0
	s_waitcnt lgkmcnt(1)
	v_cmp_ne_u32_e32 vcc, 0, v2
	s_cbranch_vccnz .LBB0_1021
	s_add_u32 s2, s92, 0x80200
	s_addc_u32 s3, s93, 0
	s_add_u32 s4, s92, 0x80400
	s_addc_u32 s5, s93, 0
	s_add_u32 s6, s92, 0x80500
	s_addc_u32 s7, s93, 0
	s_add_u32 s8, s92, 0x80600
	s_addc_u32 s9, s93, 0
	s_add_u32 s10, s92, 0x80700
	s_addc_u32 s11, s93, 0
	s_add_u32 s12, s92, 0x80800
	s_addc_u32 s13, s93, 0
	s_add_u32 s14, s92, 0x80900
	s_addc_u32 s15, s93, 0
	s_add_u32 s16, s92, 0x80a00
	s_addc_u32 s17, s93, 0
	s_add_u32 s18, s92, 0x80b00
	s_addc_u32 s19, s93, 0
	s_add_u32 s20, s92, 0x80c00
	s_addc_u32 s21, s93, 0
	s_add_u32 s22, s92, 0x80d00
	s_addc_u32 s23, s93, 0
	s_add_u32 s24, s92, 0x80e00
	s_addc_u32 s25, s93, 0
	s_add_u32 s26, s92, 0x80f00
	s_addc_u32 s27, s93, 0
	s_add_u32 s28, s92, 0x81000
	s_addc_u32 s29, s93, 0
	s_add_u32 s30, s92, 0x81100
	s_addc_u32 s31, s93, 0
	s_add_u32 s34, s92, 0x81200
	s_addc_u32 s35, s93, 0
	s_mul_i32 s33, s95, s69
	s_add_u32 s36, s92, 0x81300
	s_mul_i32 s33, s33, s94
	s_addc_u32 s37, s93, 0
	s_mov_b32 s44, 1
	v_mov_b32_e32 v16, 0
	s_branch .LBB0_1009
